# attention: next-tile LDS writes spread early over sub-tile 0, barrier moved later in PV segment, static setprio 1 for waves 4-7
# speedup vs baseline: 1.0154x; 1.0137x over previous
; #define LAS __attribute__((address_space(3)))
; #define AT_LOAD(K0, K1, V0, V1, T) do { const size_t e_ = (size_t)(128 * (T) + sr) * 64 + sc; \
;         K0 = *(const bf16x8*)(kcp + e_); V0 = *(const bf16x8*)(vcp + e_); K1 = *(const bf16x8*)(kcp + e_ + 64 * 64); V1 = *(const bf16x8*)(vcp + e_ + 64 * 64); } while (0)
; #define AT_STORE(K0, K1, V0, V1, BUF) do { *(LAS bf16x8*)(lds + AT_K + (BUF) * AT_KB + kst0) = K0; *(LAS bf16x8*)(lds + AT_K + (BUF) * AT_KB + kst1) = K1; \
;         *(LAS bf16x8*)(lds + AT_V + (BUF) * AT_VB + vst0) = V0; *(LAS bf16x8*)(lds + AT_V + (BUF) * AT_VB + vst1) = V1; } while (0)
; template <int VAR>
; __device__ __forceinline__ void attn_unit(const Args& a, int l, int b, int h, int qrow0  , bool ctxu, const bf16* Z, bf16* Y, LAS unsigned char* lds) {
;     ...
;     AT_LOAD(ka0, ka1, va0, va1, 0); AT_LOAD(kb0, kb1, vb0_, vb1_, 1); AT_STORE(ka0, ka1, va0, va1, 0);
;     const LAS unsigned char* Kb0 = lds + AT_K + comp * 64;
;     for (int t = 0; t < NT; t += 2) {
;         __syncthreads();
;         if (t + 2 < NT) AT_LOAD(ka0, ka1, va0, va1, t + 2);
;         attn_tile(Kb0, vb0, q0, q1, negm, m, o0, o1, lacc, t == 0, wsf, r32, hi);
.LBB0_431:
	v_mov_b32_e32 v79, 0
	v_readfirstlane_b32 s36, v230
	v_readfirstlane_b32 s37, v231
	s_mov_b64 s[94:95], -1
	s_mov_b32 s93, 3
	s_mov_b32 s33, 0
	v_subrev_u32_e32 v200, s36, v230
	v_add_u32_e32 v201, 0x2000, v200
	s_add_u32 s36, s36, 0x1c008000
	s_addc_u32 s37, s37, 0
	s_add_u32 s48, s36, 0x1200000
	s_addc_u32 s49, s37, 0
	s_waitcnt lgkmcnt(0)
	s_barrier
	global_load_dwordx4 v[128:131], v200, s[36:37]
	global_load_dwordx4 v[132:135], v200, s[48:49]
	global_load_dwordx4 v[144:147], v201, s[36:37]
	global_load_dwordx4 v[148:151], v201, s[48:49]
	s_add_u32 s36, s36, 0x4000
	s_addc_u32 s37, s37, 0
	s_add_u32 s48, s48, 0x4000
	s_addc_u32 s49, s49, 0
	ds_read_b128 v[48:51], v235 offset:0
	ds_read_b128 v[52:55], v235 offset:32
	ds_read_b128 v[56:59], v235 offset:4608
	ds_read_b128 v[60:63], v235 offset:4640
	s_cmp_eq_u32 s8, 1
	s_cbranch_scc0 .Lat_noprio
	s_setprio 1
.Lat_noprio:
.Lat_loop:
	s_waitcnt lgkmcnt(0)
	v_mfma_f32_32x32x16_bf16 v[96:111], v[48:51], v[136:139], v[64:79]
	ds_read_b64_tr_b16 v[168:169], v249 offset:0
	ds_read_b64_tr_b16 v[170:171], v249 offset:1024
	ds_read_b64_tr_b16 v[172:173], v249 offset:512
	ds_read_b64_tr_b16 v[174:175], v249 offset:1536
	v_mfma_f32_32x32x16_bf16 v[96:111], v[52:55], v[140:143], v[96:111]
	ds_read_b64_tr_b16 v[176:177], v249 offset:2048
	ds_read_b64_tr_b16 v[178:179], v249 offset:3072
	ds_read_b64_tr_b16 v[180:181], v249 offset:2560
	ds_read_b64_tr_b16 v[182:183], v249 offset:3584
	v_mfma_f32_32x32x16_bf16 v[112:127], v[56:59], v[136:139], v[64:79]
	ds_read_b64_tr_b16 v[184:185], v249 offset:4096
	ds_read_b64_tr_b16 v[186:187], v249 offset:5120
	ds_read_b64_tr_b16 v[188:189], v249 offset:4608
	ds_read_b64_tr_b16 v[190:191], v249 offset:5632
	v_mfma_f32_32x32x16_bf16 v[112:127], v[60:63], v[140:143], v[112:127]
	ds_read_b64_tr_b16 v[192:193], v249 offset:6144
	ds_read_b64_tr_b16 v[194:195], v249 offset:7168
	ds_read_b64_tr_b16 v[196:197], v249 offset:6656
	ds_read_b64_tr_b16 v[198:199], v249 offset:7680
	ds_read_b128 v[80:83], v235 offset:9216
	ds_read_b128 v[84:87], v235 offset:9248
	ds_read_b128 v[88:91], v235 offset:13824
	ds_read_b128 v[92:95], v235 offset:13856
	v_max3_f32 v34, v96, v97, v98
	v_max3_f32 v35, v99, v100, v101
	v_max3_f32 v34, v34, v102, v103
	v_max3_f32 v35, v35, v104, v105
	v_max3_f32 v34, v34, v106, v107
	v_max3_f32 v35, v35, v108, v109
	v_max3_f32 v34, v34, v110, v111
	v_max3_f32 v35, v35, v112, v113
	v_max3_f32 v34, v34, v114, v115
	v_max3_f32 v35, v35, v116, v117
	v_max3_f32 v34, v34, v118, v119
	v_max3_f32 v35, v35, v120, v121
	v_max3_f32 v34, v34, v122, v123
	v_max3_f32 v35, v35, v124, v125
	v_max3_f32 v34, v34, v126, v127
	v_max_f32_e32 v34, v34, v35
	v_mov_b32_e32 v35, v34
	s_nop 1
	v_permlane32_swap_b32_e32 v34, v35
	v_max_f32_e32 v34, v34, v35
	s_cmp_lg_u64 s[94:95], 0
	s_cbranch_scc1 .Lat_rare0
	v_cmp_lt_f32_e32 vcc, s4, v34
	s_cbranch_vccnz .Lat_rare0
.Lat_back0:
	s_waitcnt vmcnt(4)
	v_exp_f32_e32 v96, v96
	v_exp_f32_e32 v97, v97
	v_exp_f32_e32 v98, v98
	v_exp_f32_e32 v99, v99
	v_exp_f32_e32 v100, v100
	v_exp_f32_e32 v101, v101
	v_exp_f32_e32 v102, v102
	v_exp_f32_e32 v103, v103
	v_cvt_pk_bf16_f32 v40, v96, v97
	v_cvt_pk_bf16_f32 v41, v98, v99
	v_cvt_pk_bf16_f32 v42, v100, v101
	v_cvt_pk_bf16_f32 v43, v102, v103
	v_pk_add_f32 v[32:33], v[32:33], v[96:97]
	v_pk_add_f32 v[32:33], v[32:33], v[98:99]
	v_pk_add_f32 v[32:33], v[32:33], v[100:101]
	v_pk_add_f32 v[32:33], v[32:33], v[102:103]
	s_waitcnt lgkmcnt(15)
	v_mfma_f32_32x32x16_bf16 v[0:15], v[40:43], v[168:171], v[0:15]
	v_exp_f32_e32 v104, v104
	v_exp_f32_e32 v105, v105
	v_exp_f32_e32 v106, v106
	v_exp_f32_e32 v107, v107
	v_mfma_f32_32x32x16_bf16 v[16:31], v[40:43], v[172:175], v[16:31]
	ds_write_b128 v250, v[152:155] offset:18432
	v_exp_f32_e32 v108, v108
	v_exp_f32_e32 v109, v109
	v_exp_f32_e32 v110, v110
	v_exp_f32_e32 v111, v111
	v_cvt_pk_bf16_f32 v44, v104, v105
	v_cvt_pk_bf16_f32 v45, v106, v107
	v_cvt_pk_bf16_f32 v46, v108, v109
	v_cvt_pk_bf16_f32 v47, v110, v111
	v_pk_add_f32 v[32:33], v[32:33], v[104:105]
	v_pk_add_f32 v[32:33], v[32:33], v[106:107]
	v_pk_add_f32 v[32:33], v[32:33], v[108:109]
	v_pk_add_f32 v[32:33], v[32:33], v[110:111]
	s_waitcnt lgkmcnt(13)
	v_mfma_f32_32x32x16_bf16 v[0:15], v[44:47], v[176:179], v[0:15]
	v_exp_f32_e32 v112, v112
	v_exp_f32_e32 v113, v113
	v_exp_f32_e32 v114, v114
	v_exp_f32_e32 v115, v115
	v_mfma_f32_32x32x16_bf16 v[16:31], v[44:47], v[180:183], v[16:31]
	ds_write_b128 v250, v[160:163] offset:27648
	v_exp_f32_e32 v116, v116
	v_exp_f32_e32 v117, v117
	v_exp_f32_e32 v118, v118
	v_exp_f32_e32 v119, v119
	v_cvt_pk_bf16_f32 v40, v112, v113
	v_cvt_pk_bf16_f32 v41, v114, v115
	v_cvt_pk_bf16_f32 v42, v116, v117
	v_cvt_pk_bf16_f32 v43, v118, v119
	v_pk_add_f32 v[32:33], v[32:33], v[112:113]
	v_pk_add_f32 v[32:33], v[32:33], v[114:115]
	v_pk_add_f32 v[32:33], v[32:33], v[116:117]
	v_pk_add_f32 v[32:33], v[32:33], v[118:119]
	s_waitcnt lgkmcnt(10)
	v_mfma_f32_32x32x16_bf16 v[0:15], v[40:43], v[184:187], v[0:15]
	v_exp_f32_e32 v120, v120
	v_exp_f32_e32 v121, v121
	v_exp_f32_e32 v122, v122
	v_exp_f32_e32 v123, v123
	v_mfma_f32_32x32x16_bf16 v[16:31], v[40:43], v[188:191], v[16:31]
	ds_write_b128 v251, v[156:159] offset:53248
	v_exp_f32_e32 v124, v124
	v_exp_f32_e32 v125, v125
	v_exp_f32_e32 v126, v126
	v_exp_f32_e32 v127, v127
	v_cvt_pk_bf16_f32 v44, v120, v121
	v_cvt_pk_bf16_f32 v45, v122, v123
	v_cvt_pk_bf16_f32 v46, v124, v125
	v_cvt_pk_bf16_f32 v47, v126, v127
	v_pk_add_f32 v[32:33], v[32:33], v[120:121]
	v_pk_add_f32 v[32:33], v[32:33], v[122:123]
	v_pk_add_f32 v[32:33], v[32:33], v[124:125]
	v_pk_add_f32 v[32:33], v[32:33], v[126:127]
	s_waitcnt lgkmcnt(7)
	v_mfma_f32_32x32x16_bf16 v[0:15], v[44:47], v[192:195], v[0:15]
	v_mfma_f32_32x32x16_bf16 v[16:31], v[44:47], v[196:199], v[16:31]
	ds_write_b128 v229, v[164:167] offset:53248
	s_waitcnt lgkmcnt(4)
	v_mfma_f32_32x32x16_bf16 v[96:111], v[80:83], v[136:139], v[64:79]
	ds_read_b64_tr_b16 v[168:169], v249 offset:8192
	ds_read_b64_tr_b16 v[170:171], v249 offset:9216
	ds_read_b64_tr_b16 v[172:173], v249 offset:8704
	ds_read_b64_tr_b16 v[174:175], v249 offset:9728
	v_mfma_f32_32x32x16_bf16 v[96:111], v[84:87], v[140:143], v[96:111]
	ds_read_b64_tr_b16 v[176:177], v249 offset:10240
	ds_read_b64_tr_b16 v[178:179], v249 offset:11264
	ds_read_b64_tr_b16 v[180:181], v249 offset:10752
	ds_read_b64_tr_b16 v[182:183], v249 offset:11776
	v_mfma_f32_32x32x16_bf16 v[112:127], v[88:91], v[136:139], v[64:79]
	ds_read_b64_tr_b16 v[184:185], v249 offset:12288
	ds_read_b64_tr_b16 v[186:187], v249 offset:13312
	ds_read_b64_tr_b16 v[188:189], v249 offset:12800
	ds_read_b64_tr_b16 v[190:191], v249 offset:13824
	v_mfma_f32_32x32x16_bf16 v[112:127], v[92:95], v[140:143], v[112:127]
	ds_read_b64_tr_b16 v[192:193], v249 offset:14336
	ds_read_b64_tr_b16 v[194:195], v249 offset:15360
	ds_read_b64_tr_b16 v[196:197], v249 offset:14848
	ds_read_b64_tr_b16 v[198:199], v249 offset:15872
	v_max3_f32 v34, v96, v97, v98
	v_max3_f32 v35, v99, v100, v101
	v_max3_f32 v34, v34, v102, v103
	v_max3_f32 v35, v35, v104, v105
	v_max3_f32 v34, v34, v106, v107
	v_max3_f32 v35, v35, v108, v109
	v_max3_f32 v34, v34, v110, v111
	s_nop 1
	v_max3_f32 v35, v35, v112, v113
	v_max3_f32 v34, v34, v114, v115
	v_max3_f32 v35, v35, v116, v117
	v_max3_f32 v34, v34, v118, v119
	v_max3_f32 v35, v35, v120, v121
	v_max3_f32 v34, v34, v122, v123
	v_max3_f32 v35, v35, v124, v125
	v_max3_f32 v34, v34, v126, v127
	v_max_f32_e32 v34, v34, v35
	v_mov_b32_e32 v35, v34
	s_nop 1
	v_permlane32_swap_b32_e32 v34, v35
	v_max_f32_e32 v34, v34, v35
	v_cmp_lt_f32_e32 vcc, s4, v34
	s_cbranch_vccnz .Lat_rare1
.Lat_back1:
	v_exp_f32_e32 v96, v96
	v_exp_f32_e32 v97, v97
	v_exp_f32_e32 v98, v98
	v_exp_f32_e32 v99, v99
	v_exp_f32_e32 v100, v100
	v_exp_f32_e32 v101, v101
	v_exp_f32_e32 v102, v102
	v_exp_f32_e32 v103, v103
	v_cvt_pk_bf16_f32 v40, v96, v97
	v_cvt_pk_bf16_f32 v41, v98, v99
	v_cvt_pk_bf16_f32 v42, v100, v101
	v_cvt_pk_bf16_f32 v43, v102, v103
	v_pk_add_f32 v[32:33], v[32:33], v[96:97]
	v_pk_add_f32 v[32:33], v[32:33], v[98:99]
	v_pk_add_f32 v[32:33], v[32:33], v[100:101]
	v_pk_add_f32 v[32:33], v[32:33], v[102:103]
	s_waitcnt lgkmcnt(12)
	v_mfma_f32_32x32x16_bf16 v[0:15], v[40:43], v[168:171], v[0:15]
	v_exp_f32_e32 v104, v104
	v_exp_f32_e32 v105, v105
	v_exp_f32_e32 v106, v106
	v_exp_f32_e32 v107, v107
	v_mfma_f32_32x32x16_bf16 v[16:31], v[40:43], v[172:175], v[16:31]
	v_exp_f32_e32 v108, v108
	v_exp_f32_e32 v109, v109
	v_exp_f32_e32 v110, v110
	v_exp_f32_e32 v111, v111
	v_cvt_pk_bf16_f32 v44, v104, v105
	v_cvt_pk_bf16_f32 v45, v106, v107
	v_cvt_pk_bf16_f32 v46, v108, v109
	v_cvt_pk_bf16_f32 v47, v110, v111
	v_pk_add_f32 v[32:33], v[32:33], v[104:105]
	v_pk_add_f32 v[32:33], v[32:33], v[106:107]
	v_pk_add_f32 v[32:33], v[32:33], v[108:109]
	v_pk_add_f32 v[32:33], v[32:33], v[110:111]
	s_waitcnt lgkmcnt(8)
	v_mfma_f32_32x32x16_bf16 v[0:15], v[44:47], v[176:179], v[0:15]
	v_exp_f32_e32 v112, v112
	v_exp_f32_e32 v113, v113
	v_exp_f32_e32 v114, v114
	v_exp_f32_e32 v115, v115
	v_mfma_f32_32x32x16_bf16 v[16:31], v[44:47], v[180:183], v[16:31]
	v_exp_f32_e32 v116, v116
	v_exp_f32_e32 v117, v117
	v_exp_f32_e32 v118, v118
	v_exp_f32_e32 v119, v119
	v_cvt_pk_bf16_f32 v40, v112, v113
	v_cvt_pk_bf16_f32 v41, v114, v115
	v_cvt_pk_bf16_f32 v42, v116, v117
	v_cvt_pk_bf16_f32 v43, v118, v119
	v_pk_add_f32 v[32:33], v[32:33], v[112:113]
	v_pk_add_f32 v[32:33], v[32:33], v[114:115]
	v_pk_add_f32 v[32:33], v[32:33], v[116:117]
	v_pk_add_f32 v[32:33], v[32:33], v[118:119]
	s_waitcnt lgkmcnt(4)
	v_mfma_f32_32x32x16_bf16 v[0:15], v[40:43], v[184:187], v[0:15]
	v_exp_f32_e32 v120, v120
	v_exp_f32_e32 v121, v121
	v_exp_f32_e32 v122, v122
	v_exp_f32_e32 v123, v123
	v_mfma_f32_32x32x16_bf16 v[16:31], v[40:43], v[188:191], v[16:31]
	v_exp_f32_e32 v124, v124
	v_exp_f32_e32 v125, v125
	v_exp_f32_e32 v126, v126
	v_exp_f32_e32 v127, v127
	v_cvt_pk_bf16_f32 v44, v120, v121
	v_cvt_pk_bf16_f32 v45, v122, v123
	v_cvt_pk_bf16_f32 v46, v124, v125
	v_cvt_pk_bf16_f32 v47, v126, v127
	v_pk_add_f32 v[32:33], v[32:33], v[120:121]
	v_pk_add_f32 v[32:33], v[32:33], v[122:123]
	v_pk_add_f32 v[32:33], v[32:33], v[124:125]
	v_pk_add_f32 v[32:33], v[32:33], v[126:127]
	s_waitcnt lgkmcnt(0)
	s_barrier
; #define AT_LOAD(K0, K1, V0, V1, T) do { const size_t e_ = (size_t)(128 * (T) + sr) * 64 + sc; \
;         K0 = *(const bf16x8*)(kcp + e_); V0 = *(const bf16x8*)(vcp + e_); K1 = *(const bf16x8*)(kcp + e_ + 64 * 64); V1 = *(const bf16x8*)(vcp + e_ + 64 * 64); } while (0)
; #define AT_STORE(K0, K1, V0, V1, BUF) do { *(LAS bf16x8*)(lds + AT_K + (BUF) * AT_KB + kst0) = K0; *(LAS bf16x8*)(lds + AT_K + (BUF) * AT_KB + kst1) = K1; \
;         *(LAS bf16x8*)(lds + AT_V + (BUF) * AT_VB + vst0) = V0; *(LAS bf16x8*)(lds + AT_V + (BUF) * AT_VB + vst1) = V1; } while (0)
; template <int VAR>
; __device__ __forceinline__ void attn_unit(const Args& a, int l, int b, int h, int qrow0  , bool ctxu, const bf16* Z, bf16* Y, LAS unsigned char* lds) {
;     ...
;         __syncthreads();
;         if (t + 2 < NT) AT_LOAD(ka0, ka1, va0, va1, t + 2);
;         attn_tile(Kb0, vb0, q0, q1, negm, m, o0, o1, lacc, t == 0, wsf, r32, hi);
;         AT_STORE(kb0, kb1, vb0_, vb1_, 1);
;         __syncthreads();
;         if (t + 3 < NT) AT_LOAD(kb0, kb1, vb0_, vb1_, t + 3);
;         attn_tile(Kb0 + AT_KB, vb0 + AT_VB, q0, q1, negm, m, o0, o1, lacc, false, wsf, r32, hi);
;         if (t + 2 < NT) AT_STORE(ka0, ka1, va0, va1, 0);
	global_load_dwordx4 v[152:155], v200, s[36:37]
	global_load_dwordx4 v[156:159], v200, s[48:49]
	global_load_dwordx4 v[160:163], v201, s[36:37]
	global_load_dwordx4 v[164:167], v201, s[48:49]
	s_cmp_lt_u32 s93, 65
	s_cselect_b32 s50, 0x4000, 0
	s_add_u32 s36, s36, s50
	s_addc_u32 s37, s37, 0
	s_add_u32 s48, s48, s50
	s_addc_u32 s49, s49, 0
	s_add_u32 s93, s93, 1
	ds_read_b128 v[48:51], v235 offset:18432
	ds_read_b128 v[52:55], v235 offset:18464
	ds_read_b128 v[56:59], v235 offset:23040
	ds_read_b128 v[60:63], v235 offset:23072
	v_mfma_f32_32x32x16_bf16 v[0:15], v[44:47], v[192:195], v[0:15]
	v_mfma_f32_32x32x16_bf16 v[16:31], v[44:47], v[196:199], v[16:31]
	s_waitcnt lgkmcnt(0)
	v_mfma_f32_32x32x16_bf16 v[96:111], v[48:51], v[136:139], v[64:79]
	ds_read_b64_tr_b16 v[168:169], v233 offset:0
	ds_read_b64_tr_b16 v[170:171], v233 offset:1024
	ds_read_b64_tr_b16 v[172:173], v233 offset:512
	ds_read_b64_tr_b16 v[174:175], v233 offset:1536
	v_mfma_f32_32x32x16_bf16 v[96:111], v[52:55], v[140:143], v[96:111]
	ds_read_b64_tr_b16 v[176:177], v233 offset:2048
	ds_read_b64_tr_b16 v[178:179], v233 offset:3072
	ds_read_b64_tr_b16 v[180:181], v233 offset:2560
	ds_read_b64_tr_b16 v[182:183], v233 offset:3584
	v_mfma_f32_32x32x16_bf16 v[112:127], v[56:59], v[136:139], v[64:79]
	ds_read_b64_tr_b16 v[184:185], v233 offset:4096
	ds_read_b64_tr_b16 v[186:187], v233 offset:5120
	ds_read_b64_tr_b16 v[188:189], v233 offset:4608
	ds_read_b64_tr_b16 v[190:191], v233 offset:5632
	v_mfma_f32_32x32x16_bf16 v[112:127], v[60:63], v[140:143], v[112:127]
	ds_read_b64_tr_b16 v[192:193], v233 offset:6144
	ds_read_b64_tr_b16 v[194:195], v233 offset:7168
	ds_read_b64_tr_b16 v[196:197], v233 offset:6656
	ds_read_b64_tr_b16 v[198:199], v233 offset:7680
	ds_read_b128 v[80:83], v235 offset:27648
	ds_read_b128 v[84:87], v235 offset:27680
	ds_read_b128 v[88:91], v235 offset:32256
	ds_read_b128 v[92:95], v235 offset:32288
	v_max3_f32 v34, v96, v97, v98
	v_max3_f32 v35, v99, v100, v101
	v_max3_f32 v34, v34, v102, v103
	v_max3_f32 v35, v35, v104, v105
	v_max3_f32 v34, v34, v106, v107
	v_max3_f32 v35, v35, v108, v109
	v_max3_f32 v34, v34, v110, v111
	v_max3_f32 v35, v35, v112, v113
	v_max3_f32 v34, v34, v114, v115
	v_max3_f32 v35, v35, v116, v117
	v_max3_f32 v34, v34, v118, v119
	v_max3_f32 v35, v35, v120, v121
	v_max3_f32 v34, v34, v122, v123
	v_max3_f32 v35, v35, v124, v125
	v_max3_f32 v34, v34, v126, v127
	v_max_f32_e32 v34, v34, v35
	v_mov_b32_e32 v35, v34
	s_nop 1
	v_permlane32_swap_b32_e32 v34, v35
	v_max_f32_e32 v34, v34, v35
	v_cmp_lt_f32_e32 vcc, s4, v34
	s_cbranch_vccnz .Lat_rare2
.Lat_back2:
	s_waitcnt vmcnt(4)
	v_exp_f32_e32 v96, v96
	v_exp_f32_e32 v97, v97
	v_exp_f32_e32 v98, v98
	v_exp_f32_e32 v99, v99
	v_exp_f32_e32 v100, v100
	v_exp_f32_e32 v101, v101
	v_exp_f32_e32 v102, v102
	v_exp_f32_e32 v103, v103
	v_cvt_pk_bf16_f32 v40, v96, v97
	v_cvt_pk_bf16_f32 v41, v98, v99
	v_cvt_pk_bf16_f32 v42, v100, v101
	v_cvt_pk_bf16_f32 v43, v102, v103
	v_pk_add_f32 v[32:33], v[32:33], v[96:97]
	v_pk_add_f32 v[32:33], v[32:33], v[98:99]
	v_pk_add_f32 v[32:33], v[32:33], v[100:101]
	v_pk_add_f32 v[32:33], v[32:33], v[102:103]
	s_waitcnt lgkmcnt(15)
	v_mfma_f32_32x32x16_bf16 v[0:15], v[40:43], v[168:171], v[0:15]
	v_exp_f32_e32 v104, v104
	v_exp_f32_e32 v105, v105
	v_exp_f32_e32 v106, v106
	v_exp_f32_e32 v107, v107
	v_mfma_f32_32x32x16_bf16 v[16:31], v[40:43], v[172:175], v[16:31]
	ds_write_b128 v250, v[128:131] offset:0
	v_exp_f32_e32 v108, v108
	v_exp_f32_e32 v109, v109
	v_exp_f32_e32 v110, v110
	v_exp_f32_e32 v111, v111
	v_cvt_pk_bf16_f32 v44, v104, v105
	v_cvt_pk_bf16_f32 v45, v106, v107
	v_cvt_pk_bf16_f32 v46, v108, v109
	v_cvt_pk_bf16_f32 v47, v110, v111
	v_pk_add_f32 v[32:33], v[32:33], v[104:105]
	v_pk_add_f32 v[32:33], v[32:33], v[106:107]
	v_pk_add_f32 v[32:33], v[32:33], v[108:109]
	v_pk_add_f32 v[32:33], v[32:33], v[110:111]
	s_waitcnt lgkmcnt(13)
	v_mfma_f32_32x32x16_bf16 v[0:15], v[44:47], v[176:179], v[0:15]
	v_exp_f32_e32 v112, v112
	v_exp_f32_e32 v113, v113
	v_exp_f32_e32 v114, v114
	v_exp_f32_e32 v115, v115
	v_mfma_f32_32x32x16_bf16 v[16:31], v[44:47], v[180:183], v[16:31]
	ds_write_b128 v250, v[144:147] offset:9216
	v_exp_f32_e32 v116, v116
	v_exp_f32_e32 v117, v117
	v_exp_f32_e32 v118, v118
	v_exp_f32_e32 v119, v119
	v_cvt_pk_bf16_f32 v40, v112, v113
	v_cvt_pk_bf16_f32 v41, v114, v115
	v_cvt_pk_bf16_f32 v42, v116, v117
	v_cvt_pk_bf16_f32 v43, v118, v119
	v_pk_add_f32 v[32:33], v[32:33], v[112:113]
	v_pk_add_f32 v[32:33], v[32:33], v[114:115]
	v_pk_add_f32 v[32:33], v[32:33], v[116:117]
	v_pk_add_f32 v[32:33], v[32:33], v[118:119]
	s_waitcnt lgkmcnt(10)
	v_mfma_f32_32x32x16_bf16 v[0:15], v[40:43], v[184:187], v[0:15]
	v_exp_f32_e32 v120, v120
	v_exp_f32_e32 v121, v121
	v_exp_f32_e32 v122, v122
	v_exp_f32_e32 v123, v123
	v_mfma_f32_32x32x16_bf16 v[16:31], v[40:43], v[188:191], v[16:31]
	ds_write_b128 v251, v[132:135] offset:36864
	v_exp_f32_e32 v124, v124
	v_exp_f32_e32 v125, v125
	v_exp_f32_e32 v126, v126
	v_exp_f32_e32 v127, v127
	v_cvt_pk_bf16_f32 v44, v120, v121
	v_cvt_pk_bf16_f32 v45, v122, v123
	v_cvt_pk_bf16_f32 v46, v124, v125
	v_cvt_pk_bf16_f32 v47, v126, v127
	v_pk_add_f32 v[32:33], v[32:33], v[120:121]
	v_pk_add_f32 v[32:33], v[32:33], v[122:123]
	v_pk_add_f32 v[32:33], v[32:33], v[124:125]
	v_pk_add_f32 v[32:33], v[32:33], v[126:127]
	s_waitcnt lgkmcnt(7)
	v_mfma_f32_32x32x16_bf16 v[0:15], v[44:47], v[192:195], v[0:15]
	v_mfma_f32_32x32x16_bf16 v[16:31], v[44:47], v[196:199], v[16:31]
	ds_write_b128 v229, v[148:151] offset:36864
	s_waitcnt lgkmcnt(4)
; #define AT_LOAD(K0, K1, V0, V1, T) do { const size_t e_ = (size_t)(128 * (T) + sr) * 64 + sc; \
;         K0 = *(const bf16x8*)(kcp + e_); V0 = *(const bf16x8*)(vcp + e_); K1 = *(const bf16x8*)(kcp + e_ + 64 * 64); V1 = *(const bf16x8*)(vcp + e_ + 64 * 64); } while (0)
; #define AT_STORE(K0, K1, V0, V1, BUF) do { *(LAS bf16x8*)(lds + AT_K + (BUF) * AT_KB + kst0) = K0; *(LAS bf16x8*)(lds + AT_K + (BUF) * AT_KB + kst1) = K1; \
;         *(LAS bf16x8*)(lds + AT_V + (BUF) * AT_VB + vst0) = V0; *(LAS bf16x8*)(lds + AT_V + (BUF) * AT_VB + vst1) = V1; } while (0)
; template <int VAR>
; __device__ __forceinline__ void attn_unit(const Args& a, int l, int b, int h, int qrow0  , bool ctxu, const bf16* Z, bf16* Y, LAS unsigned char* lds) {
;     ...
;         AT_STORE(kb0, kb1, vb0_, vb1_, 1);
;         __syncthreads();
;         if (t + 3 < NT) AT_LOAD(kb0, kb1, vb0_, vb1_, t + 3);
;         attn_tile(Kb0 + AT_KB, vb0 + AT_VB, q0, q1, negm, m, o0, o1, lacc, false, wsf, r32, hi);
;         if (t + 2 < NT) AT_STORE(ka0, ka1, va0, va1, 0);
;     }
	v_mfma_f32_32x32x16_bf16 v[96:111], v[80:83], v[136:139], v[64:79]
	ds_read_b64_tr_b16 v[168:169], v233 offset:8192
	ds_read_b64_tr_b16 v[170:171], v233 offset:9216
	ds_read_b64_tr_b16 v[172:173], v233 offset:8704
	ds_read_b64_tr_b16 v[174:175], v233 offset:9728
	v_mfma_f32_32x32x16_bf16 v[96:111], v[84:87], v[140:143], v[96:111]
	ds_read_b64_tr_b16 v[176:177], v233 offset:10240
	ds_read_b64_tr_b16 v[178:179], v233 offset:11264
	ds_read_b64_tr_b16 v[180:181], v233 offset:10752
	ds_read_b64_tr_b16 v[182:183], v233 offset:11776
	v_mfma_f32_32x32x16_bf16 v[112:127], v[88:91], v[136:139], v[64:79]
	ds_read_b64_tr_b16 v[184:185], v233 offset:12288
	ds_read_b64_tr_b16 v[186:187], v233 offset:13312
	ds_read_b64_tr_b16 v[188:189], v233 offset:12800
	ds_read_b64_tr_b16 v[190:191], v233 offset:13824
	v_mfma_f32_32x32x16_bf16 v[112:127], v[92:95], v[140:143], v[112:127]
	ds_read_b64_tr_b16 v[192:193], v233 offset:14336
	ds_read_b64_tr_b16 v[194:195], v233 offset:15360
	ds_read_b64_tr_b16 v[196:197], v233 offset:14848
	ds_read_b64_tr_b16 v[198:199], v233 offset:15872
	v_max3_f32 v34, v96, v97, v98
	v_max3_f32 v35, v99, v100, v101
	v_max3_f32 v34, v34, v102, v103
	v_max3_f32 v35, v35, v104, v105
	v_max3_f32 v34, v34, v106, v107
	v_max3_f32 v35, v35, v108, v109
	v_max3_f32 v34, v34, v110, v111
	s_nop 1
	v_max3_f32 v35, v35, v112, v113
	v_max3_f32 v34, v34, v114, v115
	v_max3_f32 v35, v35, v116, v117
	v_max3_f32 v34, v34, v118, v119
	v_max3_f32 v35, v35, v120, v121
	v_max3_f32 v34, v34, v122, v123
	v_max3_f32 v35, v35, v124, v125
	v_max3_f32 v34, v34, v126, v127
	v_max_f32_e32 v34, v34, v35
	v_mov_b32_e32 v35, v34
	s_nop 1
	v_permlane32_swap_b32_e32 v34, v35
	v_max_f32_e32 v34, v34, v35
	v_cmp_lt_f32_e32 vcc, s4, v34
	s_cbranch_vccnz .Lat_rare3
.Lat_back3:
	v_exp_f32_e32 v96, v96
	v_exp_f32_e32 v97, v97
	v_exp_f32_e32 v98, v98
	v_exp_f32_e32 v99, v99
	v_exp_f32_e32 v100, v100
	v_exp_f32_e32 v101, v101
	v_exp_f32_e32 v102, v102
	v_exp_f32_e32 v103, v103
	v_cvt_pk_bf16_f32 v40, v96, v97
	v_cvt_pk_bf16_f32 v41, v98, v99
	v_cvt_pk_bf16_f32 v42, v100, v101
	v_cvt_pk_bf16_f32 v43, v102, v103
	v_pk_add_f32 v[32:33], v[32:33], v[96:97]
	v_pk_add_f32 v[32:33], v[32:33], v[98:99]
	v_pk_add_f32 v[32:33], v[32:33], v[100:101]
	v_pk_add_f32 v[32:33], v[32:33], v[102:103]
	s_waitcnt lgkmcnt(12)
	v_mfma_f32_32x32x16_bf16 v[0:15], v[40:43], v[168:171], v[0:15]
	v_exp_f32_e32 v104, v104
	v_exp_f32_e32 v105, v105
	v_exp_f32_e32 v106, v106
	v_exp_f32_e32 v107, v107
	v_mfma_f32_32x32x16_bf16 v[16:31], v[40:43], v[172:175], v[16:31]
	v_exp_f32_e32 v108, v108
	v_exp_f32_e32 v109, v109
	v_exp_f32_e32 v110, v110
	v_exp_f32_e32 v111, v111
	v_cvt_pk_bf16_f32 v44, v104, v105
	v_cvt_pk_bf16_f32 v45, v106, v107
	v_cvt_pk_bf16_f32 v46, v108, v109
	v_cvt_pk_bf16_f32 v47, v110, v111
	v_pk_add_f32 v[32:33], v[32:33], v[104:105]
	v_pk_add_f32 v[32:33], v[32:33], v[106:107]
	v_pk_add_f32 v[32:33], v[32:33], v[108:109]
	v_pk_add_f32 v[32:33], v[32:33], v[110:111]
	s_waitcnt lgkmcnt(8)
	v_mfma_f32_32x32x16_bf16 v[0:15], v[44:47], v[176:179], v[0:15]
	v_exp_f32_e32 v112, v112
	v_exp_f32_e32 v113, v113
	v_exp_f32_e32 v114, v114
	v_exp_f32_e32 v115, v115
	v_mfma_f32_32x32x16_bf16 v[16:31], v[44:47], v[180:183], v[16:31]
	v_exp_f32_e32 v116, v116
	v_exp_f32_e32 v117, v117
	v_exp_f32_e32 v118, v118
	v_exp_f32_e32 v119, v119
	v_cvt_pk_bf16_f32 v40, v112, v113
	v_cvt_pk_bf16_f32 v41, v114, v115
	v_cvt_pk_bf16_f32 v42, v116, v117
	v_cvt_pk_bf16_f32 v43, v118, v119
	v_pk_add_f32 v[32:33], v[32:33], v[112:113]
	v_pk_add_f32 v[32:33], v[32:33], v[114:115]
	v_pk_add_f32 v[32:33], v[32:33], v[116:117]
	v_pk_add_f32 v[32:33], v[32:33], v[118:119]
	s_waitcnt lgkmcnt(4)
	v_mfma_f32_32x32x16_bf16 v[0:15], v[40:43], v[184:187], v[0:15]
	v_exp_f32_e32 v120, v120
	v_exp_f32_e32 v121, v121
	v_exp_f32_e32 v122, v122
	v_exp_f32_e32 v123, v123
	v_mfma_f32_32x32x16_bf16 v[16:31], v[40:43], v[188:191], v[16:31]
	v_exp_f32_e32 v124, v124
	v_exp_f32_e32 v125, v125
	v_exp_f32_e32 v126, v126
	v_exp_f32_e32 v127, v127
	v_cvt_pk_bf16_f32 v44, v120, v121
	v_cvt_pk_bf16_f32 v45, v122, v123
	v_cvt_pk_bf16_f32 v46, v124, v125
	v_cvt_pk_bf16_f32 v47, v126, v127
	v_pk_add_f32 v[32:33], v[32:33], v[120:121]
	v_pk_add_f32 v[32:33], v[32:33], v[122:123]
	v_pk_add_f32 v[32:33], v[32:33], v[124:125]
	v_pk_add_f32 v[32:33], v[32:33], v[126:127]
	s_waitcnt lgkmcnt(0)
	s_barrier
	global_load_dwordx4 v[128:131], v200, s[36:37]
	global_load_dwordx4 v[132:135], v200, s[48:49]
	global_load_dwordx4 v[144:147], v201, s[36:37]
	global_load_dwordx4 v[148:151], v201, s[48:49]
	s_cmp_lt_u32 s93, 65
	s_cselect_b32 s50, 0x4000, 0
	s_add_u32 s36, s36, s50
	s_addc_u32 s37, s37, 0
	s_add_u32 s48, s48, s50
	s_addc_u32 s49, s49, 0
	s_add_u32 s93, s93, 1
	ds_read_b128 v[48:51], v235 offset:0
	ds_read_b128 v[52:55], v235 offset:32
	ds_read_b128 v[56:59], v235 offset:4608
	ds_read_b128 v[60:63], v235 offset:4640
	v_mfma_f32_32x32x16_bf16 v[0:15], v[44:47], v[192:195], v[0:15]
	v_mfma_f32_32x32x16_bf16 v[16:31], v[44:47], v[196:199], v[16:31]
	s_add_u32 s33, s33, 2
	s_cmp_lt_u32 s33, 66
	s_cbranch_scc1 .Lat_loop
	v_add_f32_e32 v34, v32, v33
	v_add_u32_e32 v36, s31, v216
	v_mov_b32_e32 v35, v34
	s_nop 1
	v_permlane32_swap_b32_e32 v34, v35
	v_add_f32_e32 v37, v34, v35
	s_waitcnt lgkmcnt(0)
	ds_write_b32 v232, v37
	s_waitcnt lgkmcnt(0)
	v_mov_b32_e32 v48, v36
	ds_read_b128 v[32:35], v48 offset:0
	ds_read_b128 v[36:39], v48 offset:32
	ds_read_b128 v[40:43], v48 offset:64
	ds_read_b128 v[44:47], v48 offset:96
	s_waitcnt vmcnt(0) lgkmcnt(0)
	s_setprio 0
	s_branch .LBB0_459
